# attention loop: straight-line K/V LDS-DMA issue (no out-of-line branch pairs), literal threshold compare
# baseline (speedup 1.0000x reference)
; #define AT_DMA(t, buf) do { _Pragma("unroll") for (int j_ = 0; j_ < 7; ++j_) { const int c_ = wid + 8 * j_; if (c_ < 50) { \
;             __builtin_amdgcn_global_load_lds((const unsigned*)dsrc[j_], (LAS unsigned*)(lds + (buf) * AT_BUF + 1024 * c_), 16, 0, 0); dsrc[j_] += dstr[j_]; } } } while (0)
; __device__ __forceinline__ void attn_unit(const Params& P, LAS unsigned char* lds, int bh, int qb) {
;     ...
;         const int buf = t & 1; const bool more = (t + 1 < NT);
;         if (more) AT_DMA(t + 1, buf ^ 1);
.LBB0_633:
	s_add_i32 s0, s94, -1
	s_and_b32 s0, s0, 1
	s_cmp_ge_u32 s94, s83
	s_cbranch_scc1 .LBB0_642
	s_xor_b32 s1, s0, 1
	s_mul_i32 s1, s1, 0xc800
	s_add_i32 s53, s1, s82
	s_mov_b32 m0, s53
	s_nop 0
	global_load_lds_dwordx4 v[176:177], off
	s_add_i32 m0, s53, 0x2000
	v_lshl_add_u64 v[176:177], v[176:177], 0, v[178:179]
	global_load_lds_dwordx4 v[180:181], off
	s_add_i32 m0, s53, 0x4000
	v_lshl_add_u64 v[180:181], v[180:181], 0, v[182:183]
	global_load_lds_dwordx4 v[184:185], off
	s_add_i32 m0, s53, 0x6000
	v_lshl_add_u64 v[184:185], v[184:185], 0, v[186:187]
	global_load_lds_dwordx4 v[188:189], off
	s_add_i32 m0, s53, 0x8000
	v_lshl_add_u64 v[188:189], v[188:189], 0, v[190:191]
	global_load_lds_dwordx4 v[192:193], off
	s_add_i32 m0, s53, 0xa000
	v_lshl_add_u64 v[192:193], v[192:193], 0, v[194:195]
	global_load_lds_dwordx4 v[196:197], off
	v_lshl_add_u64 v[196:197], v[196:197], 0, v[198:199]
	s_andn2_b64 vcc, exec, s[74:75]
	s_cbranch_vccnz .LBB0_642
	s_add_i32 m0, s53, 0xc000
	s_nop 0
	global_load_lds_dwordx4 v[200:201], off
	v_lshl_add_u64 v[200:201], v[200:201], 0, v[202:203]

; __device__ __forceinline__ float xmax16(float m) { const auto r = __builtin_amdgcn_permlane16_swap(__float_as_uint(m), __float_as_uint(m), false, false); return fmaxf(__uint_as_float(r[0]), __uint_as_float(r[1])); }
; __device__ __forceinline__ float xmax32(float m) { const auto r = __builtin_amdgcn_permlane32_swap(__float_as_uint(m), __float_as_uint(m), false, false); return fmaxf(__uint_as_float(r[0]), __uint_as_float(r[1])); }
; __device__ __forceinline__ void attn_unit(const Params& P, LAS unsigned char* lds, int bh, int qb) {
;     ...
;             float mx[2];
; #pragma unroll
;             for (int qk = 0; qk < 2; ++qk) { float m_ = fmaxf(fmaxf(s[0][qk][0], s[0][qk][1]), fmaxf(s[0][qk][2], s[0][qk][3]));
; #pragma unroll
;                 for (int kvb = 1; kvb < 4; ++kvb) m_ = fmaxf(m_, fmaxf(fmaxf(s[kvb][qk][0], s[kvb][qk][1]), fmaxf(s[kvb][qk][2], s[kvb][qk][3])));
;                 m_ = xmax16(m_); m_ = xmax32(m_); mx[qk] = m_; }
;             if (t == 0 || __any((mx[0] > AT_THR) || (mx[1] > AT_THR))) {
.LBB0_645:
	v_max3_f32 v207, v164, v165, v166
	v_max3_f32 v206, v148, v149, v150
	v_max3_f32 v207, v207, v167, v160
	v_max3_f32 v206, v206, v151, v144
	v_max3_f32 v207, v207, v161, v162
	v_max3_f32 v206, v206, v145, v146
	v_max3_f32 v207, v207, v163, v156
	v_max3_f32 v206, v206, v147, v140
	v_max3_f32 v207, v207, v157, v158
	v_max3_f32 v206, v206, v141, v142
	v_max3_f32 v207, v207, v159, v152
	v_max3_f32 v206, v206, v143, v136
	v_max3_f32 v207, v207, v153, v154
	v_max3_f32 v206, v206, v137, v138
	v_max_f32_e32 v207, v207, v155
	v_max_f32_e32 v206, v206, v139
	s_cmp_eq_u32 s85, 0
	s_cbranch_scc1 .Latt_slowmax
	v_max_f32_e32 v225, v207, v206
	v_cmp_lt_f32_e32 vcc, 0x41000000, v225
	s_cbranch_vccz .LBB0_631

; __device__ __forceinline__ void attn_unit(const Params& P, LAS unsigned char* lds, int bh, int qb) {
;     ...
;             if (t == 0 || __any((mx[0] > AT_THR) || (mx[1] > AT_THR))) {
; #pragma unroll
;                 for (int qk = 0; qk < 2; ++qk) { const float dl = (t == 0) ? mx[qk] : fmaxf(mx[qk], 0.f), alpha = __builtin_amdgcn_exp2f(-dl); mrow[qk] += dl; lacc[qk] *= alpha;
; #pragma unroll
;                     for (int kvb = 0; kvb < 4; ++kvb) s[kvb][qk] -= dl;
; #pragma unroll
;                     for (int dvb = 0; dvb < 8; ++dvb) o[dvb][qk] *= alpha; }
;             }
.LBB0_648:
	s_and_b64 vcc, exec, s[54:55]
	s_cbranch_vccz .LBB0_631
	v_max_f32_e32 v224, 0, v224
	v_cndmask_b32_e64 v206, v224, v206, s[0:1]
	v_exp_f32_e64 v226, -v207
	v_exp_f32_e64 v224, -v206
	v_sub_f32_e32 v164, v164, v207
	v_sub_f32_e32 v165, v165, v207
	v_pk_mul_f32 v[114:115], v[114:115], v[226:227] op_sel_hi:[1,0]
	v_pk_mul_f32 v[112:113], v[112:113], v[226:227] op_sel_hi:[1,0]
	v_sub_f32_e32 v166, v166, v207
	v_sub_f32_e32 v167, v167, v207
	v_sub_f32_e32 v160, v160, v207
	v_sub_f32_e32 v161, v161, v207
	v_sub_f32_e32 v162, v162, v207
	v_sub_f32_e32 v163, v163, v207
	v_sub_f32_e32 v156, v156, v207
	v_sub_f32_e32 v157, v157, v207
	v_sub_f32_e32 v158, v158, v207
	v_sub_f32_e32 v159, v159, v207
	v_sub_f32_e32 v152, v152, v207
	v_sub_f32_e32 v153, v153, v207
	v_sub_f32_e32 v154, v154, v207
	v_sub_f32_e32 v155, v155, v207
	v_pk_mul_f32 v[118:119], v[118:119], v[226:227] op_sel_hi:[1,0]
	v_pk_mul_f32 v[116:117], v[116:117], v[226:227] op_sel_hi:[1,0]
	v_pk_mul_f32 v[110:111], v[110:111], v[226:227] op_sel_hi:[1,0]
	v_pk_mul_f32 v[108:109], v[108:109], v[226:227] op_sel_hi:[1,0]
	v_pk_mul_f32 v[106:107], v[106:107], v[226:227] op_sel_hi:[1,0]
	v_pk_mul_f32 v[104:105], v[104:105], v[226:227] op_sel_hi:[1,0]
	v_pk_mul_f32 v[102:103], v[102:103], v[226:227] op_sel_hi:[1,0]
	v_pk_mul_f32 v[100:101], v[100:101], v[226:227] op_sel_hi:[1,0]
	v_pk_mul_f32 v[98:99], v[98:99], v[226:227] op_sel_hi:[1,0]
	v_pk_mul_f32 v[96:97], v[96:97], v[226:227] op_sel_hi:[1,0]
	v_pk_mul_f32 v[94:95], v[94:95], v[226:227] op_sel_hi:[1,0]
	v_pk_mul_f32 v[92:93], v[92:93], v[226:227] op_sel_hi:[1,0]
	v_pk_mul_f32 v[90:91], v[90:91], v[226:227] op_sel_hi:[1,0]
	v_pk_mul_f32 v[88:89], v[88:89], v[226:227] op_sel_hi:[1,0]
	v_pk_mul_f32 v[74:75], v[74:75], v[226:227] op_sel_hi:[1,0]
	v_pk_mul_f32 v[72:73], v[72:73], v[226:227] op_sel_hi:[1,0]
	v_pk_add_f32 v[204:205], v[204:205], v[206:207]
	v_xor_b32_e32 v244, 0x80000000, v205
	v_xor_b32_e32 v248, 0x80000000, v204
	v_mov_b32_e32 v245, v244
	v_mov_b32_e32 v246, v244
	v_mov_b32_e32 v247, v244
	v_mov_b32_e32 v249, v248
	v_mov_b32_e32 v250, v248
	v_mov_b32_e32 v251, v248
	v_pk_mul_f32 v[78:79], v[78:79], v[224:225] op_sel_hi:[1,0]
	v_pk_mul_f32 v[76:77], v[76:77], v[224:225] op_sel_hi:[1,0]
	v_sub_f32_e32 v148, v148, v206
	v_sub_f32_e32 v149, v149, v206
	v_sub_f32_e32 v150, v150, v206
	v_sub_f32_e32 v151, v151, v206
	v_sub_f32_e32 v144, v144, v206
	v_sub_f32_e32 v145, v145, v206
	v_sub_f32_e32 v146, v146, v206
	v_sub_f32_e32 v147, v147, v206
	v_sub_f32_e32 v140, v140, v206
	v_sub_f32_e32 v141, v141, v206
	v_sub_f32_e32 v142, v142, v206
	v_sub_f32_e32 v143, v143, v206
	v_sub_f32_e32 v136, v136, v206
	v_sub_f32_e32 v137, v137, v206
	v_sub_f32_e32 v138, v138, v206
	v_sub_f32_e32 v139, v139, v206
	v_pk_mul_f32 v[86:87], v[86:87], v[224:225] op_sel_hi:[1,0]
	v_pk_mul_f32 v[84:85], v[84:85], v[224:225] op_sel_hi:[1,0]
	v_pk_mul_f32 v[82:83], v[82:83], v[224:225] op_sel_hi:[1,0]
	v_pk_mul_f32 v[80:81], v[80:81], v[224:225] op_sel_hi:[1,0]
	v_pk_mul_f32 v[70:71], v[70:71], v[224:225] op_sel_hi:[1,0]
	v_pk_mul_f32 v[68:69], v[68:69], v[224:225] op_sel_hi:[1,0]
	v_pk_mul_f32 v[66:67], v[66:67], v[224:225] op_sel_hi:[1,0]
	v_pk_mul_f32 v[64:65], v[64:65], v[224:225] op_sel_hi:[1,0]
	v_pk_mul_f32 v[62:63], v[62:63], v[224:225] op_sel_hi:[1,0]
	v_pk_mul_f32 v[60:61], v[60:61], v[224:225] op_sel_hi:[1,0]
	v_pk_mul_f32 v[58:59], v[58:59], v[224:225] op_sel_hi:[1,0]
	v_pk_mul_f32 v[56:57], v[56:57], v[224:225] op_sel_hi:[1,0]
	v_pk_mul_f32 v[54:55], v[54:55], v[224:225] op_sel_hi:[1,0]
	v_pk_mul_f32 v[52:53], v[52:53], v[224:225] op_sel_hi:[1,0]
	v_pk_mul_f32 v[50:51], v[50:51], v[224:225] op_sel_hi:[1,0]
	v_pk_mul_f32 v[48:49], v[48:49], v[224:225] op_sel_hi:[1,0]
	s_branch .LBB0_631
.LBB0_656:
	s_branch .LBB0_631
